# P0 FFN-in weight transpose: 32 loads in flight instead of hipcc serialized load-wait chain; P7 loads pipelined
# speedup vs baseline: 1.0620x; 1.0120x over previous
; #define LAS __attribute__((address_space(3)))
; __device__ __forceinline__ void p0_transpose_item(const float* W, int ldw, int k0, int n0, bf16_t* WT, int ldt, int dst_row0, LAS float* scr, int lane, const float* kscale = nullptr) {
; #pragma unroll
;     for (int i = 0; i < 32; ++i) { const int kk = 2 * i + (lane >> 5); scr[kk * 33 + (lane & 31)] = W[(size_t)(k0 + kk) * ldw + n0 + (lane & 31)] * (kscale ? kscale[k0 + kk] : 1.f); }
; __device__ __forceinline__ void p0_phase(const Args& a, LAS unsigned char* lds, int tid, int lane, int wave) {
;     ...
;         if (r < I_FFI) { const int nb = 2 * DFF / 32, kb = r / nb, n0 = (r % nb) * 32; const int nn = n0 < DFF ? n0 : n0 - DFF; const int drow = (nn >> 7) * 256 + (n0 < DFF ? 0 : 128) + (nn & 127);
;             p0_transpose_item(a.in[22], 2 * DFF, kb * 64, n0, (bf16_t*)(ws + WS_WFFI), D, drow, scr, lane, a.in[21]); continue; } r -= I_FFI;
.LBB0_62:
	s_andn2_b64 vcc, exec, s[2:3]
	s_cbranch_vccnz .LBB0_128
	v_readlane_b32 s34, v254, 15
	v_readlane_b32 s35, v254, 16
	s_add_i32 s0, s8, 0xffffec00
	s_mul_i32 s2, s0, 0xba2f
	s_lshr_b32 s2, s2, 23
	s_mul_i32 s3, s2, 0xb0
	s_sub_i32 s7, s0, s3
	s_lshl_b32 s6, s2, 6
	s_lshl_b32 s0, s7, 7
	v_lshl_add_u64 v[26:27], v[16:17], 0, s[0:1]
	v_and_b32_e32 v240, 7, v132
	v_lshl_or_b32 v240, v240, 3, s6
	v_lshlrev_b32_e32 v240, 2, v240
	global_load_dwordx4 v[232:235], v240, s[34:35]
	global_load_dwordx4 v[236:239], v240, s[34:35] offset:16
	v_or_b32_e32 v0, s6, v28
	v_mad_u64_u32 v[136:137], s[32:33], v0, s14, v[26:27]
	v_or_b32_e32 v0, s6, v31
	v_mad_u64_u32 v[138:139], s[32:33], v0, s14, v[26:27]
	v_or_b32_e32 v0, s6, v32
	v_mad_u64_u32 v[140:141], s[32:33], v0, s14, v[26:27]
	v_or_b32_e32 v0, s6, v33
	v_mad_u64_u32 v[142:143], s[32:33], v0, s14, v[26:27]
	v_or_b32_e32 v0, s6, v34
	v_mad_u64_u32 v[144:145], s[32:33], v0, s14, v[26:27]
	v_or_b32_e32 v0, s6, v35
	v_mad_u64_u32 v[146:147], s[32:33], v0, s14, v[26:27]
	v_or_b32_e32 v0, s6, v36
	v_mad_u64_u32 v[148:149], s[32:33], v0, s14, v[26:27]
	v_or_b32_e32 v0, s6, v38
	v_mad_u64_u32 v[150:151], s[32:33], v0, s14, v[26:27]
	v_or_b32_e32 v0, s6, v39
	v_mad_u64_u32 v[152:153], s[32:33], v0, s14, v[26:27]
	v_or_b32_e32 v0, s6, v40
	v_mad_u64_u32 v[154:155], s[32:33], v0, s14, v[26:27]
	v_or_b32_e32 v0, s6, v66
	v_mad_u64_u32 v[156:157], s[32:33], v0, s14, v[26:27]
	v_or_b32_e32 v0, s6, v67
	v_mad_u64_u32 v[158:159], s[32:33], v0, s14, v[26:27]
	v_or_b32_e32 v0, s6, v68
	v_mad_u64_u32 v[160:161], s[32:33], v0, s14, v[26:27]
	v_or_b32_e32 v0, s6, v69
	v_mad_u64_u32 v[162:163], s[32:33], v0, s14, v[26:27]
	v_or_b32_e32 v0, s6, v70
	v_mad_u64_u32 v[164:165], s[32:33], v0, s14, v[26:27]
	v_or_b32_e32 v0, s6, v71
	v_mad_u64_u32 v[166:167], s[32:33], v0, s14, v[26:27]
	v_or_b32_e32 v0, s6, v72
	v_mad_u64_u32 v[168:169], s[32:33], v0, s14, v[26:27]
	v_or_b32_e32 v0, s6, v73
	v_mad_u64_u32 v[170:171], s[32:33], v0, s14, v[26:27]
	v_or_b32_e32 v0, s6, v74
	v_mad_u64_u32 v[172:173], s[32:33], v0, s14, v[26:27]
	v_or_b32_e32 v0, s6, v75
	v_mad_u64_u32 v[174:175], s[32:33], v0, s14, v[26:27]
	v_or_b32_e32 v0, s6, v76
	v_mad_u64_u32 v[176:177], s[32:33], v0, s14, v[26:27]
	v_or_b32_e32 v0, s6, v77
	v_mad_u64_u32 v[178:179], s[32:33], v0, s14, v[26:27]
	v_or_b32_e32 v0, s6, v78
	v_mad_u64_u32 v[180:181], s[32:33], v0, s14, v[26:27]
	v_or_b32_e32 v0, s6, v79
	v_mad_u64_u32 v[182:183], s[32:33], v0, s14, v[26:27]
	v_or_b32_e32 v0, s6, v80
	v_mad_u64_u32 v[184:185], s[32:33], v0, s14, v[26:27]
	v_or_b32_e32 v0, s6, v81
	v_mad_u64_u32 v[186:187], s[32:33], v0, s14, v[26:27]
	v_or_b32_e32 v0, s6, v82
	v_mad_u64_u32 v[188:189], s[32:33], v0, s14, v[26:27]
	v_or_b32_e32 v0, s6, v83
	v_mad_u64_u32 v[190:191], s[32:33], v0, s14, v[26:27]
	v_or_b32_e32 v0, s6, v84
	v_mad_u64_u32 v[192:193], s[32:33], v0, s14, v[26:27]
	v_or_b32_e32 v0, s6, v85
	v_mad_u64_u32 v[194:195], s[32:33], v0, s14, v[26:27]
	v_or_b32_e32 v0, s6, v86
	v_mad_u64_u32 v[196:197], s[32:33], v0, s14, v[26:27]
	v_or_b32_e32 v0, s6, v87
	v_mad_u64_u32 v[198:199], s[32:33], v0, s14, v[26:27]
	global_load_dword v200, v[136:137], off
	global_load_dword v201, v[138:139], off
	global_load_dword v202, v[140:141], off
	global_load_dword v203, v[142:143], off
	global_load_dword v204, v[144:145], off
	global_load_dword v205, v[146:147], off
	global_load_dword v206, v[148:149], off
	global_load_dword v207, v[150:151], off
	global_load_dword v208, v[152:153], off
	global_load_dword v209, v[154:155], off
	global_load_dword v210, v[156:157], off
	global_load_dword v211, v[158:159], off
	global_load_dword v212, v[160:161], off
	global_load_dword v213, v[162:163], off
	global_load_dword v214, v[164:165], off
	global_load_dword v215, v[166:167], off
	global_load_dword v216, v[168:169], off
	global_load_dword v217, v[170:171], off
	global_load_dword v218, v[172:173], off
	global_load_dword v219, v[174:175], off
	global_load_dword v220, v[176:177], off
	global_load_dword v221, v[178:179], off
	global_load_dword v222, v[180:181], off
	global_load_dword v223, v[182:183], off
	global_load_dword v224, v[184:185], off
	global_load_dword v225, v[186:187], off
	global_load_dword v226, v[188:189], off
	global_load_dword v227, v[190:191], off
	global_load_dword v228, v[192:193], off
	global_load_dword v229, v[194:195], off
	global_load_dword v230, v[196:197], off
	global_load_dword v231, v[198:199], off
	v_add_u32_e32 v0, v29, v30
	s_waitcnt vmcnt(30)
	ds_write2_b32 v0, v200, v201 offset1:66
	s_waitcnt vmcnt(28)
	ds_write2_b32 v0, v202, v203 offset0:132 offset1:198
	v_add_u32_e32 v0, 0x400, v0
	s_waitcnt vmcnt(26)
; #define LAS __attribute__((address_space(3)))
; __device__ __forceinline__ unsigned cvt_pk_bf16(float lo, float hi) { unsigned r; asm volatile("v_cvt_pk_bf16_f32 %0, %1, %2" : "=v"(r) : "v"(lo), "v"(hi)); return r; }
; __device__ __forceinline__ void p0_transpose_item(const float* W, int ldw, int k0, int n0, bf16_t* WT, int ldt, int dst_row0, LAS float* scr, int lane, const float* kscale = nullptr) {
;     ...
;     for (int i = 0; i < 32; ++i) { const int kk = 2 * i + (lane >> 5); scr[kk * 33 + (lane & 31)] = W[(size_t)(k0 + kk) * ldw + n0 + (lane & 31)] * (kscale ? kscale[k0 + kk] : 1.f); }
;     asm volatile("s_waitcnt lgkmcnt(0)" ::: "memory");
;     const int c = lane & 7;
; #pragma unroll
;     for (int j = 0; j < 4; ++j) { const int n = (lane >> 3) + 8 * j; const LAS float* s = scr + (8 * c) * 33 + n;
;         u32x4 o; o.x = cvt_pk_bf16(s[0 * 33], s[1 * 33]); o.y = cvt_pk_bf16(s[2 * 33], s[3 * 33]); o.z = cvt_pk_bf16(s[4 * 33], s[5 * 33]); o.w = cvt_pk_bf16(s[6 * 33], s[7 * 33]);
;         *(u32x4*)(WT + (size_t)(dst_row0 + n) * ldt + k0 + 8 * c) = o; }
;     asm volatile("s_waitcnt lgkmcnt(0)" ::: "memory");
	ds_write2_b32 v0, v204, v205 offset0:8 offset1:74
	v_add_u32_e32 v0, v29, v37
	s_waitcnt vmcnt(24)
	ds_write2_b32 v0, v206, v207 offset1:66
	s_waitcnt vmcnt(22)
	ds_write2_b32 v0, v208, v209 offset0:132 offset1:198
	v_add_u32_e32 v0, 0x400, v0
	s_waitcnt vmcnt(20)
	ds_write2_b32 v0, v210, v211 offset0:8 offset1:74
	v_add_u32_e32 v0, v29, v41
	s_waitcnt vmcnt(18)
	ds_write2_b32 v0, v212, v213 offset1:66
	s_waitcnt vmcnt(16)
	ds_write2_b32 v0, v214, v215 offset0:132 offset1:198
	v_add_u32_e32 v0, 0x400, v0
	s_waitcnt vmcnt(14)
	ds_write2_b32 v0, v216, v217 offset0:8 offset1:74
	v_add_u32_e32 v0, v29, v42
	s_waitcnt vmcnt(12)
	ds_write2_b32 v0, v218, v219 offset1:66
	s_waitcnt vmcnt(10)
	ds_write2_b32 v0, v220, v221 offset0:132 offset1:198
	v_add_u32_e32 v0, 0x400, v0
	s_waitcnt vmcnt(8)
	ds_write2_b32 v0, v222, v223 offset0:8 offset1:74
	v_add_u32_e32 v0, v29, v43
	s_waitcnt vmcnt(6)
	ds_write2_b32 v0, v224, v225 offset1:66
	s_waitcnt vmcnt(4)
	ds_write2_b32 v0, v226, v227 offset0:132 offset1:198
	v_add_u32_e32 v0, 0x400, v0
	s_waitcnt vmcnt(2)
	ds_write2_b32 v0, v228, v229 offset0:8 offset1:74
	s_waitcnt vmcnt(0)
	ds_write2_b32 v0, v230, v231 offset0:140 offset1:206
	s_lshl_b32 s0, s7, 5
	s_add_i32 s3, s0, 0xfffff500
	s_cmpk_lt_u32 s7, 0x58
	s_cselect_b32 s0, s0, s3
	s_cselect_b32 s2, 0, 0x80
	s_lshl_b32 s3, s0, 1
	s_and_b32 s0, s0, 0x60
	s_and_b32 s3, s3, 0xffffff00
	s_or_b32 s0, s0, s2
	s_or_b32 s2, s0, s3
	s_lshl_b32 s0, s6, 1
	v_lshl_add_u64 v[96:97], v[4:5], 0, s[0:1]
	s_waitcnt lgkmcnt(0)
	ds_read2_b32 v[136:137], v45 offset1:33
	ds_read2_b32 v[138:139], v45 offset0:66 offset1:99
	ds_read2_b32 v[140:141], v45 offset0:132 offset1:165
	ds_read2_b32 v[142:143], v45 offset0:198 offset1:231
	ds_read2_b32 v[144:145], v45 offset0:8 offset1:41
	ds_read2_b32 v[146:147], v45 offset0:74 offset1:107
	ds_read2_b32 v[148:149], v45 offset0:140 offset1:173
	ds_read2_b32 v[150:151], v45 offset0:206 offset1:239
	ds_read2_b32 v[152:153], v45 offset0:16 offset1:49
	ds_read2_b32 v[154:155], v45 offset0:82 offset1:115
	ds_read2_b32 v[156:157], v45 offset0:148 offset1:181
	ds_read2_b32 v[158:159], v45 offset0:214 offset1:247
	ds_read2_b32 v[160:161], v45 offset0:24 offset1:57
	ds_read2_b32 v[162:163], v45 offset0:90 offset1:123
	ds_read2_b32 v[164:165], v45 offset0:156 offset1:189
	ds_read2_b32 v[166:167], v45 offset0:222 offset1:255
	s_waitcnt lgkmcnt(0)
	v_mul_f32_e32 v136, v136, v232
	v_mul_f32_e32 v137, v137, v233
	v_mul_f32_e32 v138, v138, v234
	v_mul_f32_e32 v139, v139, v235
	v_mul_f32_e32 v140, v140, v236
	v_mul_f32_e32 v141, v141, v237
	v_mul_f32_e32 v142, v142, v238
	v_mul_f32_e32 v143, v143, v239
	v_cvt_pk_bf16_f32 v168, v136, v137
	v_cvt_pk_bf16_f32 v169, v138, v139
	v_cvt_pk_bf16_f32 v170, v140, v141
	v_cvt_pk_bf16_f32 v171, v142, v143
	v_or_b32_e32 v26, s2, v44
	v_ashrrev_i32_e32 v27, 31, v26
	v_lshlrev_b64 v[26:27], 11, v[26:27]
	v_lshl_add_u64 v[26:27], v[96:97], 0, v[26:27]
	global_store_dwordx4 v[26:27], v[168:171], off
	v_mul_f32_e32 v144, v144, v232
	v_mul_f32_e32 v145, v145, v233
	v_mul_f32_e32 v146, v146, v234
	v_mul_f32_e32 v147, v147, v235
	v_mul_f32_e32 v148, v148, v236
	v_mul_f32_e32 v149, v149, v237
	v_mul_f32_e32 v150, v150, v238
	v_mul_f32_e32 v151, v151, v239
	v_cvt_pk_bf16_f32 v172, v144, v145
	v_cvt_pk_bf16_f32 v173, v146, v147
	v_cvt_pk_bf16_f32 v174, v148, v149
	v_cvt_pk_bf16_f32 v175, v150, v151
	v_or_b32_e32 v26, s2, v88
	v_ashrrev_i32_e32 v27, 31, v26
	v_lshlrev_b64 v[26:27], 11, v[26:27]
	v_lshl_add_u64 v[26:27], v[96:97], 0, v[26:27]
	global_store_dwordx4 v[26:27], v[172:175], off
	v_mul_f32_e32 v152, v152, v232
	v_mul_f32_e32 v153, v153, v233
	v_mul_f32_e32 v154, v154, v234
	v_mul_f32_e32 v155, v155, v235
	v_mul_f32_e32 v156, v156, v236
	v_mul_f32_e32 v157, v157, v237
	v_mul_f32_e32 v158, v158, v238
	v_mul_f32_e32 v159, v159, v239
	v_cvt_pk_bf16_f32 v176, v152, v153
	v_cvt_pk_bf16_f32 v177, v154, v155
	v_cvt_pk_bf16_f32 v178, v156, v157
	v_cvt_pk_bf16_f32 v179, v158, v159
	v_or_b32_e32 v26, s2, v89
	v_ashrrev_i32_e32 v27, 31, v26
	v_lshlrev_b64 v[26:27], 11, v[26:27]
	v_lshl_add_u64 v[26:27], v[96:97], 0, v[26:27]
	global_store_dwordx4 v[26:27], v[176:179], off
	v_mul_f32_e32 v160, v160, v232
	v_mul_f32_e32 v161, v161, v233
	v_mul_f32_e32 v162, v162, v234
	v_mul_f32_e32 v163, v163, v235
	v_mul_f32_e32 v164, v164, v236
	v_mul_f32_e32 v165, v165, v237
	v_mul_f32_e32 v166, v166, v238
	v_mul_f32_e32 v167, v167, v239
	v_cvt_pk_bf16_f32 v180, v160, v161
	v_cvt_pk_bf16_f32 v181, v162, v163
	v_cvt_pk_bf16_f32 v182, v164, v165
	v_cvt_pk_bf16_f32 v183, v166, v167
	v_or_b32_e32 v26, s2, v90
	v_ashrrev_i32_e32 v27, 31, v26
	v_lshlrev_b64 v[26:27], 11, v[26:27]
	v_lshl_add_u64 v[26:27], v[96:97], 0, v[26:27]
	global_store_dwordx4 v[26:27], v[180:183], off

; __global__ void __launch_bounds__(512, 2) fwd_megakernel(Args a) {
;     ...
;     if (IN(7)) {
;         const float* rss = (const float*)(ws + WS_RSS3); const float* gf = a.in[24];
;         f32x4 gv[4];
; #pragma unroll
;         for (int j = 0; j < 4; ++j) gv[j] = *(const f32x4*)(gf + 4 * lane + 256 * j);
;         for (int row = blockIdx.x * 8 + wave; row < M; row += gridDim.x * 8) {
;             const float rstd = 1.0f / sqrtf(rss[row] * (1.f / D) + EPS); float* y = a.out + O_Y + (size_t)row * D + 4 * lane; const bf16_t* x3 = (const bf16_t*)(ws + WS_XG) + (size_t)row * D + 4 * lane;
; #pragma unroll
;             for (int j = 0; j < 4; ++j) { const u32x2 w = *(const u32x2*)(x3 + 256 * j);
.LBB0_1006:
	s_or_b64 exec, exec, s[0:1]
	s_cmp_lt_i32 s90, 8
	s_cselect_b64 s[0:1], -1, 0
	s_cmp_gt_i32 s91, 7
	s_cselect_b64 s[2:3], -1, 0
	s_and_b64 s[0:1], s[0:1], s[2:3]
	s_andn2_b64 vcc, exec, s[0:1]
	s_waitcnt lgkmcnt(0)
	s_barrier
	s_cbranch_vccnz .LBB0_1010
	s_lshl_b32 s0, s44, 3
	v_readlane_b32 s1, v254, 21
	s_add_i32 s2, s1, s0
	s_cmpk_gt_i32 s2, 0x43ff
	s_cbranch_scc1 .LBB0_1010
	v_lshlrev_b32_e32 v16, 4, v132
	global_load_dwordx4 v[0:3], v16, s[84:85]
	global_load_dwordx4 v[4:7], v16, s[84:85] offset:1024
	global_load_dwordx4 v[8:11], v16, s[84:85] offset:2048
	global_load_dwordx4 v[12:15], v16, s[84:85] offset:3072
	v_mov_b32_e32 v17, 0
	v_lshl_add_u64 v[18:19], s[86:87], 0, v[16:17]
	v_lshlrev_b32_e32 v16, 3, v132
	s_add_u32 s4, s88, 0x120000
	v_lshl_add_u64 v[20:21], s[88:89], 0, v[16:17]
	s_mov_b64 s[0:1], 0x9600000
	s_addc_u32 s5, s89, 0
	v_lshl_add_u64 v[20:21], v[20:21], 0, s[0:1]
	s_lshl_b32 s6, s94, 3
	v_mov_b32_e32 v16, 0x358637bd
	s_mov_b32 s7, 0xf800000
	v_mov_b32_e32 v22, 0x260
	s_mov_b32 s3, 0
	s_mov_b32 s8, s2
	s_add_i32 s2, s8, 0x4000
	s_cmpk_lt_i32 s2, 0x4400
	s_cselect_b64 s[10:11], -1, 0
	s_cbranch_scc0 .Lp7_skip8a
	s_lshl_b64 s[0:1], s[2:3], 2
	s_add_u32 s0, s4, s0
	s_addc_u32 s1, s5, s1
	global_load_dword v120, v17, s[0:1]
	s_lshl_b64 s[0:1], s[2:3], 11
	v_lshl_add_u64 v[28:29], v[20:21], 0, s[0:1]
	global_load_dwordx2 v[104:105], v[28:29], off
	global_load_dwordx2 v[106:107], v[28:29], off offset:512
	global_load_dwordx2 v[108:109], v[28:29], off offset:1024
	global_load_dwordx2 v[110:111], v[28:29], off offset:1536
.Lp7_skip8a:
	s_mov_b32 s2, s8
	s_lshl_b64 s[0:1], s[2:3], 2
	s_add_u32 s0, s4, s0
	s_addc_u32 s1, s5, s1
	global_load_dword v112, v17, s[0:1]
	s_lshl_b64 s[0:1], s[2:3], 11
	v_lshl_add_u64 v[28:29], v[20:21], 0, s[0:1]
	global_load_dwordx2 v[40:41], v[28:29], off
	global_load_dwordx2 v[42:43], v[28:29], off offset:512
	global_load_dwordx2 v[44:45], v[28:29], off offset:1024
	global_load_dwordx2 v[46:47], v[28:29], off offset:1536
	s_add_i32 s2, s2, s6
	s_lshl_b64 s[0:1], s[2:3], 2
	s_add_u32 s0, s4, s0
	s_addc_u32 s1, s5, s1
	global_load_dword v113, v17, s[0:1]
	s_lshl_b64 s[0:1], s[2:3], 11
	v_lshl_add_u64 v[28:29], v[20:21], 0, s[0:1]
	global_load_dwordx2 v[48:49], v[28:29], off
	global_load_dwordx2 v[50:51], v[28:29], off offset:512
	global_load_dwordx2 v[52:53], v[28:29], off offset:1024
	global_load_dwordx2 v[54:55], v[28:29], off offset:1536
	s_add_i32 s2, s2, s6
	s_lshl_b64 s[0:1], s[2:3], 2
	s_add_u32 s0, s4, s0
	s_addc_u32 s1, s5, s1
	global_load_dword v114, v17, s[0:1]
	s_lshl_b64 s[0:1], s[2:3], 11
	v_lshl_add_u64 v[28:29], v[20:21], 0, s[0:1]
	global_load_dwordx2 v[56:57], v[28:29], off
	global_load_dwordx2 v[58:59], v[28:29], off offset:512
	global_load_dwordx2 v[60:61], v[28:29], off offset:1024
	global_load_dwordx2 v[62:63], v[28:29], off offset:1536
	s_add_i32 s2, s2, s6
	s_lshl_b64 s[0:1], s[2:3], 2
	s_add_u32 s0, s4, s0
	s_addc_u32 s1, s5, s1
	global_load_dword v115, v17, s[0:1]
	s_lshl_b64 s[0:1], s[2:3], 11
	v_lshl_add_u64 v[28:29], v[20:21], 0, s[0:1]
	global_load_dwordx2 v[64:65], v[28:29], off
	global_load_dwordx2 v[66:67], v[28:29], off offset:512
	global_load_dwordx2 v[68:69], v[28:29], off offset:1024
	global_load_dwordx2 v[70:71], v[28:29], off offset:1536
	s_add_i32 s2, s2, s6
	s_lshl_b64 s[0:1], s[2:3], 2
	s_add_u32 s0, s4, s0
	s_addc_u32 s1, s5, s1
	global_load_dword v116, v17, s[0:1]
	s_lshl_b64 s[0:1], s[2:3], 11
	v_lshl_add_u64 v[28:29], v[20:21], 0, s[0:1]
	global_load_dwordx2 v[72:73], v[28:29], off
	global_load_dwordx2 v[74:75], v[28:29], off offset:512
	global_load_dwordx2 v[76:77], v[28:29], off offset:1024
	global_load_dwordx2 v[78:79], v[28:29], off offset:1536
	s_add_i32 s2, s2, s6
	s_lshl_b64 s[0:1], s[2:3], 2
	s_add_u32 s0, s4, s0
	s_addc_u32 s1, s5, s1
	global_load_dword v117, v17, s[0:1]
	s_lshl_b64 s[0:1], s[2:3], 11
	v_lshl_add_u64 v[28:29], v[20:21], 0, s[0:1]
	global_load_dwordx2 v[80:81], v[28:29], off
	global_load_dwordx2 v[82:83], v[28:29], off offset:512
	global_load_dwordx2 v[84:85], v[28:29], off offset:1024
	global_load_dwordx2 v[86:87], v[28:29], off offset:1536
	s_add_i32 s2, s2, s6
	s_lshl_b64 s[0:1], s[2:3], 2
	s_add_u32 s0, s4, s0
	s_addc_u32 s1, s5, s1
	global_load_dword v118, v17, s[0:1]
	s_lshl_b64 s[0:1], s[2:3], 11
	v_lshl_add_u64 v[28:29], v[20:21], 0, s[0:1]
	global_load_dwordx2 v[88:89], v[28:29], off
	global_load_dwordx2 v[90:91], v[28:29], off offset:512
	global_load_dwordx2 v[92:93], v[28:29], off offset:1024
	global_load_dwordx2 v[94:95], v[28:29], off offset:1536
	s_add_i32 s2, s2, s6
	s_lshl_b64 s[0:1], s[2:3], 2
	s_add_u32 s0, s4, s0
	s_addc_u32 s1, s5, s1
	global_load_dword v119, v17, s[0:1]
	s_lshl_b64 s[0:1], s[2:3], 11
	v_lshl_add_u64 v[28:29], v[20:21], 0, s[0:1]
	global_load_dwordx2 v[96:97], v[28:29], off
	global_load_dwordx2 v[98:99], v[28:29], off offset:512
	global_load_dwordx2 v[100:101], v[28:29], off offset:1024
	global_load_dwordx2 v[102:103], v[28:29], off offset:1536
	s_mov_b32 s2, s8
	s_waitcnt vmcnt(35)
; __global__ void __launch_bounds__(512, 2) fwd_megakernel(Args a) {
;     ...
;         for (int row = blockIdx.x * 8 + wave; row < M; row += gridDim.x * 8) {
;             const float rstd = 1.0f / sqrtf(rss[row] * (1.f / D) + EPS); float* y = a.out + O_Y + (size_t)row * D + 4 * lane; const bf16_t* x3 = (const bf16_t*)(ws + WS_XG) + (size_t)row * D + 4 * lane;
; #pragma unroll
;             for (int j = 0; j < 4; ++j) { const u32x2 w = *(const u32x2*)(x3 + 256 * j);
;                 f32x4 v = {__uint_as_float(w.x << 16), __uint_as_float(w.x & 0xffff0000u), __uint_as_float(w.y << 16), __uint_as_float(w.y & 0xffff0000u)};
;                 *(f32x4*)(y + 256 * j) = v * rstd * gv[j]; }
	v_fmamk_f32 v23, v112, 0x3a800000, v16
	v_mul_f32_e32 v26, 0x4f800000, v23
	v_cmp_gt_f32_e32 vcc, s7, v23
	s_lshl_b64 s[0:1], s[2:3], 12
	v_lshl_add_u64 v[30:31], v[18:19], 0, s[0:1]
	v_cndmask_b32_e32 v23, v23, v26, vcc
	v_sqrt_f32_e32 v32, v23
	s_nop 1
	v_add_u32_e32 v33, -1, v32
	v_add_u32_e32 v34, 1, v32
	v_fma_f32 v35, -v33, v32, v23
	v_fma_f32 v36, -v34, v32, v23
	v_cmp_ge_f32_e64 s[0:1], 0, v35
	s_nop 1
	v_cndmask_b32_e64 v32, v32, v33, s[0:1]
	v_cmp_lt_f32_e64 s[0:1], 0, v36
	s_nop 1
	v_cndmask_b32_e64 v32, v32, v34, s[0:1]
	v_mul_f32_e32 v33, 0x37800000, v32
	v_cndmask_b32_e32 v32, v32, v33, vcc
	v_cmp_class_f32_e32 vcc, v23, v22
	s_nop 1
	v_cndmask_b32_e32 v23, v32, v23, vcc
	v_div_scale_f32 v32, s[0:1], v23, v23, 1.0
	v_rcp_f32_e32 v33, v32
	v_div_scale_f32 v34, vcc, 1.0, v23, 1.0
	v_fma_f32 v35, -v32, v33, 1.0
	v_fmac_f32_e32 v33, v35, v33
	v_mul_f32_e32 v35, v34, v33
	v_fma_f32 v36, -v32, v35, v34
	v_fmac_f32_e32 v35, v36, v33
	v_fma_f32 v32, -v32, v35, v34
	v_div_fmas_f32 v32, v32, v33, v35
	v_div_fixup_f32 v32, v32, v23, 1.0
	v_lshlrev_b32_e32 v24, 16, v40
	v_and_b32_e32 v25, 0xffff0000, v40
	v_lshlrev_b32_e32 v26, 16, v41
	v_and_b32_e32 v27, 0xffff0000, v41
	v_pk_mul_f32 v[34:35], v[32:33], v[24:25] op_sel_hi:[0,1]
	v_pk_mul_f32 v[36:37], v[32:33], v[26:27] op_sel_hi:[0,1]
	v_pk_mul_f32 v[124:125], v[0:1], v[34:35]
	v_pk_mul_f32 v[126:127], v[2:3], v[36:37]
	global_store_dwordx4 v[30:31], v[124:127], off
	v_lshlrev_b32_e32 v24, 16, v42
	v_and_b32_e32 v25, 0xffff0000, v42
	v_lshlrev_b32_e32 v26, 16, v43
	v_and_b32_e32 v27, 0xffff0000, v43
	v_pk_mul_f32 v[34:35], v[32:33], v[24:25] op_sel_hi:[0,1]
	v_pk_mul_f32 v[36:37], v[32:33], v[26:27] op_sel_hi:[0,1]
	v_pk_mul_f32 v[128:129], v[4:5], v[34:35]
	v_pk_mul_f32 v[130:131], v[6:7], v[36:37]
	global_store_dwordx4 v[30:31], v[128:131], off offset:1024
	v_lshlrev_b32_e32 v24, 16, v44
	v_and_b32_e32 v25, 0xffff0000, v44
	v_lshlrev_b32_e32 v26, 16, v45
	v_and_b32_e32 v27, 0xffff0000, v45
	v_pk_mul_f32 v[34:35], v[32:33], v[24:25] op_sel_hi:[0,1]
	v_pk_mul_f32 v[36:37], v[32:33], v[26:27] op_sel_hi:[0,1]
	v_pk_mul_f32 v[132:133], v[8:9], v[34:35]
	v_pk_mul_f32 v[134:135], v[10:11], v[36:37]
	global_store_dwordx4 v[30:31], v[132:135], off offset:2048
	v_lshlrev_b32_e32 v24, 16, v46
	v_and_b32_e32 v25, 0xffff0000, v46
	v_lshlrev_b32_e32 v26, 16, v47
	v_and_b32_e32 v27, 0xffff0000, v47
	v_pk_mul_f32 v[34:35], v[32:33], v[24:25] op_sel_hi:[0,1]
	v_pk_mul_f32 v[36:37], v[32:33], v[26:27] op_sel_hi:[0,1]
	v_pk_mul_f32 v[136:137], v[12:13], v[34:35]
	v_pk_mul_f32 v[138:139], v[14:15], v[36:37]
	global_store_dwordx4 v[30:31], v[136:139], off offset:3072
	s_add_i32 s2, s2, s6
	s_waitcnt vmcnt(34)
	v_fmamk_f32 v23, v113, 0x3a800000, v16
	v_mul_f32_e32 v26, 0x4f800000, v23
	v_cmp_gt_f32_e32 vcc, s7, v23
	s_lshl_b64 s[0:1], s[2:3], 12
	v_lshl_add_u64 v[30:31], v[18:19], 0, s[0:1]
	v_cndmask_b32_e32 v23, v23, v26, vcc
	v_sqrt_f32_e32 v32, v23
	s_nop 1
	v_add_u32_e32 v33, -1, v32
	v_add_u32_e32 v34, 1, v32
	v_fma_f32 v35, -v33, v32, v23
	v_fma_f32 v36, -v34, v32, v23
	v_cmp_ge_f32_e64 s[0:1], 0, v35
	s_nop 1
	v_cndmask_b32_e64 v32, v32, v33, s[0:1]
	v_cmp_lt_f32_e64 s[0:1], 0, v36
	s_nop 1
	v_cndmask_b32_e64 v32, v32, v34, s[0:1]
	v_mul_f32_e32 v33, 0x37800000, v32
	v_cndmask_b32_e32 v32, v32, v33, vcc
	v_cmp_class_f32_e32 vcc, v23, v22
	s_nop 1
	v_cndmask_b32_e32 v23, v32, v23, vcc
	v_div_scale_f32 v32, s[0:1], v23, v23, 1.0
	v_rcp_f32_e32 v33, v32
	v_div_scale_f32 v34, vcc, 1.0, v23, 1.0
	v_fma_f32 v35, -v32, v33, 1.0
	v_fmac_f32_e32 v33, v35, v33
	v_mul_f32_e32 v35, v34, v33
	v_fma_f32 v36, -v32, v35, v34
	v_fmac_f32_e32 v35, v36, v33
	v_fma_f32 v32, -v32, v35, v34
	v_div_fmas_f32 v32, v32, v33, v35
	v_div_fixup_f32 v32, v32, v23, 1.0
	v_lshlrev_b32_e32 v24, 16, v48
	v_and_b32_e32 v25, 0xffff0000, v48
	v_lshlrev_b32_e32 v26, 16, v49
	v_and_b32_e32 v27, 0xffff0000, v49
	v_pk_mul_f32 v[34:35], v[32:33], v[24:25] op_sel_hi:[0,1]
	v_pk_mul_f32 v[36:37], v[32:33], v[26:27] op_sel_hi:[0,1]
	v_pk_mul_f32 v[124:125], v[0:1], v[34:35]
	v_pk_mul_f32 v[126:127], v[2:3], v[36:37]
	global_store_dwordx4 v[30:31], v[124:127], off
	v_lshlrev_b32_e32 v24, 16, v50
	v_and_b32_e32 v25, 0xffff0000, v50
	v_lshlrev_b32_e32 v26, 16, v51
	v_and_b32_e32 v27, 0xffff0000, v51
	v_pk_mul_f32 v[34:35], v[32:33], v[24:25] op_sel_hi:[0,1]
	v_pk_mul_f32 v[36:37], v[32:33], v[26:27] op_sel_hi:[0,1]
	v_pk_mul_f32 v[128:129], v[4:5], v[34:35]
	v_pk_mul_f32 v[130:131], v[6:7], v[36:37]
	global_store_dwordx4 v[30:31], v[128:131], off offset:1024
	v_lshlrev_b32_e32 v24, 16, v52
	v_and_b32_e32 v25, 0xffff0000, v52
	v_lshlrev_b32_e32 v26, 16, v53
	v_and_b32_e32 v27, 0xffff0000, v53
	v_pk_mul_f32 v[34:35], v[32:33], v[24:25] op_sel_hi:[0,1]
	v_pk_mul_f32 v[36:37], v[32:33], v[26:27] op_sel_hi:[0,1]
	v_pk_mul_f32 v[132:133], v[8:9], v[34:35]
	v_pk_mul_f32 v[134:135], v[10:11], v[36:37]
	global_store_dwordx4 v[30:31], v[132:135], off offset:2048
	v_lshlrev_b32_e32 v24, 16, v54
	v_and_b32_e32 v25, 0xffff0000, v54
	v_lshlrev_b32_e32 v26, 16, v55
	v_and_b32_e32 v27, 0xffff0000, v55
	v_pk_mul_f32 v[34:35], v[32:33], v[24:25] op_sel_hi:[0,1]
	v_pk_mul_f32 v[36:37], v[32:33], v[26:27] op_sel_hi:[0,1]
	v_pk_mul_f32 v[136:137], v[12:13], v[34:35]
	v_pk_mul_f32 v[138:139], v[14:15], v[36:37]
	global_store_dwordx4 v[30:31], v[136:139], off offset:3072
	s_add_i32 s2, s2, s6
	s_waitcnt vmcnt(33)
; __global__ void __launch_bounds__(512, 2) fwd_megakernel(Args a) {
;     ...
;         for (int row = blockIdx.x * 8 + wave; row < M; row += gridDim.x * 8) {
;             const float rstd = 1.0f / sqrtf(rss[row] * (1.f / D) + EPS); float* y = a.out + O_Y + (size_t)row * D + 4 * lane; const bf16_t* x3 = (const bf16_t*)(ws + WS_XG) + (size_t)row * D + 4 * lane;
; #pragma unroll
;             for (int j = 0; j < 4; ++j) { const u32x2 w = *(const u32x2*)(x3 + 256 * j);
;                 f32x4 v = {__uint_as_float(w.x << 16), __uint_as_float(w.x & 0xffff0000u), __uint_as_float(w.y << 16), __uint_as_float(w.y & 0xffff0000u)};
;                 *(f32x4*)(y + 256 * j) = v * rstd * gv[j]; }
	v_fmamk_f32 v23, v114, 0x3a800000, v16
	v_mul_f32_e32 v26, 0x4f800000, v23
	v_cmp_gt_f32_e32 vcc, s7, v23
	s_lshl_b64 s[0:1], s[2:3], 12
	v_lshl_add_u64 v[30:31], v[18:19], 0, s[0:1]
	v_cndmask_b32_e32 v23, v23, v26, vcc
	v_sqrt_f32_e32 v32, v23
	s_nop 1
	v_add_u32_e32 v33, -1, v32
	v_add_u32_e32 v34, 1, v32
	v_fma_f32 v35, -v33, v32, v23
	v_fma_f32 v36, -v34, v32, v23
	v_cmp_ge_f32_e64 s[0:1], 0, v35
	s_nop 1
	v_cndmask_b32_e64 v32, v32, v33, s[0:1]
	v_cmp_lt_f32_e64 s[0:1], 0, v36
	s_nop 1
	v_cndmask_b32_e64 v32, v32, v34, s[0:1]
	v_mul_f32_e32 v33, 0x37800000, v32
	v_cndmask_b32_e32 v32, v32, v33, vcc
	v_cmp_class_f32_e32 vcc, v23, v22
	s_nop 1
	v_cndmask_b32_e32 v23, v32, v23, vcc
	v_div_scale_f32 v32, s[0:1], v23, v23, 1.0
	v_rcp_f32_e32 v33, v32
	v_div_scale_f32 v34, vcc, 1.0, v23, 1.0
	v_fma_f32 v35, -v32, v33, 1.0
	v_fmac_f32_e32 v33, v35, v33
	v_mul_f32_e32 v35, v34, v33
	v_fma_f32 v36, -v32, v35, v34
	v_fmac_f32_e32 v35, v36, v33
	v_fma_f32 v32, -v32, v35, v34
	v_div_fmas_f32 v32, v32, v33, v35
	v_div_fixup_f32 v32, v32, v23, 1.0
	v_lshlrev_b32_e32 v24, 16, v56
	v_and_b32_e32 v25, 0xffff0000, v56
	v_lshlrev_b32_e32 v26, 16, v57
	v_and_b32_e32 v27, 0xffff0000, v57
	v_pk_mul_f32 v[34:35], v[32:33], v[24:25] op_sel_hi:[0,1]
	v_pk_mul_f32 v[36:37], v[32:33], v[26:27] op_sel_hi:[0,1]
	v_pk_mul_f32 v[124:125], v[0:1], v[34:35]
	v_pk_mul_f32 v[126:127], v[2:3], v[36:37]
	global_store_dwordx4 v[30:31], v[124:127], off
	v_lshlrev_b32_e32 v24, 16, v58
	v_and_b32_e32 v25, 0xffff0000, v58
	v_lshlrev_b32_e32 v26, 16, v59
	v_and_b32_e32 v27, 0xffff0000, v59
	v_pk_mul_f32 v[34:35], v[32:33], v[24:25] op_sel_hi:[0,1]
	v_pk_mul_f32 v[36:37], v[32:33], v[26:27] op_sel_hi:[0,1]
	v_pk_mul_f32 v[128:129], v[4:5], v[34:35]
	v_pk_mul_f32 v[130:131], v[6:7], v[36:37]
	global_store_dwordx4 v[30:31], v[128:131], off offset:1024
	v_lshlrev_b32_e32 v24, 16, v60
	v_and_b32_e32 v25, 0xffff0000, v60
	v_lshlrev_b32_e32 v26, 16, v61
	v_and_b32_e32 v27, 0xffff0000, v61
	v_pk_mul_f32 v[34:35], v[32:33], v[24:25] op_sel_hi:[0,1]
	v_pk_mul_f32 v[36:37], v[32:33], v[26:27] op_sel_hi:[0,1]
	v_pk_mul_f32 v[132:133], v[8:9], v[34:35]
	v_pk_mul_f32 v[134:135], v[10:11], v[36:37]
	global_store_dwordx4 v[30:31], v[132:135], off offset:2048
	v_lshlrev_b32_e32 v24, 16, v62
	v_and_b32_e32 v25, 0xffff0000, v62
	v_lshlrev_b32_e32 v26, 16, v63
	v_and_b32_e32 v27, 0xffff0000, v63
	v_pk_mul_f32 v[34:35], v[32:33], v[24:25] op_sel_hi:[0,1]
	v_pk_mul_f32 v[36:37], v[32:33], v[26:27] op_sel_hi:[0,1]
	v_pk_mul_f32 v[136:137], v[12:13], v[34:35]
	v_pk_mul_f32 v[138:139], v[14:15], v[36:37]
	global_store_dwordx4 v[30:31], v[136:139], off offset:3072
	s_add_i32 s2, s2, s6
	s_waitcnt vmcnt(32)
	v_fmamk_f32 v23, v115, 0x3a800000, v16
	v_mul_f32_e32 v26, 0x4f800000, v23
	v_cmp_gt_f32_e32 vcc, s7, v23
	s_lshl_b64 s[0:1], s[2:3], 12
	v_lshl_add_u64 v[30:31], v[18:19], 0, s[0:1]
	v_cndmask_b32_e32 v23, v23, v26, vcc
	v_sqrt_f32_e32 v32, v23
	s_nop 1
	v_add_u32_e32 v33, -1, v32
	v_add_u32_e32 v34, 1, v32
	v_fma_f32 v35, -v33, v32, v23
	v_fma_f32 v36, -v34, v32, v23
	v_cmp_ge_f32_e64 s[0:1], 0, v35
	s_nop 1
	v_cndmask_b32_e64 v32, v32, v33, s[0:1]
	v_cmp_lt_f32_e64 s[0:1], 0, v36
	s_nop 1
	v_cndmask_b32_e64 v32, v32, v34, s[0:1]
	v_mul_f32_e32 v33, 0x37800000, v32
	v_cndmask_b32_e32 v32, v32, v33, vcc
	v_cmp_class_f32_e32 vcc, v23, v22
	s_nop 1
	v_cndmask_b32_e32 v23, v32, v23, vcc
	v_div_scale_f32 v32, s[0:1], v23, v23, 1.0
	v_rcp_f32_e32 v33, v32
	v_div_scale_f32 v34, vcc, 1.0, v23, 1.0
	v_fma_f32 v35, -v32, v33, 1.0
	v_fmac_f32_e32 v33, v35, v33
	v_mul_f32_e32 v35, v34, v33
	v_fma_f32 v36, -v32, v35, v34
	v_fmac_f32_e32 v35, v36, v33
	v_fma_f32 v32, -v32, v35, v34
	v_div_fmas_f32 v32, v32, v33, v35
	v_div_fixup_f32 v32, v32, v23, 1.0
	v_lshlrev_b32_e32 v24, 16, v64
	v_and_b32_e32 v25, 0xffff0000, v64
	v_lshlrev_b32_e32 v26, 16, v65
	v_and_b32_e32 v27, 0xffff0000, v65
	v_pk_mul_f32 v[34:35], v[32:33], v[24:25] op_sel_hi:[0,1]
	v_pk_mul_f32 v[36:37], v[32:33], v[26:27] op_sel_hi:[0,1]
	v_pk_mul_f32 v[124:125], v[0:1], v[34:35]
	v_pk_mul_f32 v[126:127], v[2:3], v[36:37]
	global_store_dwordx4 v[30:31], v[124:127], off
	v_lshlrev_b32_e32 v24, 16, v66
	v_and_b32_e32 v25, 0xffff0000, v66
	v_lshlrev_b32_e32 v26, 16, v67
	v_and_b32_e32 v27, 0xffff0000, v67
	v_pk_mul_f32 v[34:35], v[32:33], v[24:25] op_sel_hi:[0,1]
	v_pk_mul_f32 v[36:37], v[32:33], v[26:27] op_sel_hi:[0,1]
	v_pk_mul_f32 v[128:129], v[4:5], v[34:35]
	v_pk_mul_f32 v[130:131], v[6:7], v[36:37]
	global_store_dwordx4 v[30:31], v[128:131], off offset:1024
	v_lshlrev_b32_e32 v24, 16, v68
	v_and_b32_e32 v25, 0xffff0000, v68
	v_lshlrev_b32_e32 v26, 16, v69
	v_and_b32_e32 v27, 0xffff0000, v69
	v_pk_mul_f32 v[34:35], v[32:33], v[24:25] op_sel_hi:[0,1]
	v_pk_mul_f32 v[36:37], v[32:33], v[26:27] op_sel_hi:[0,1]
	v_pk_mul_f32 v[132:133], v[8:9], v[34:35]
	v_pk_mul_f32 v[134:135], v[10:11], v[36:37]
	global_store_dwordx4 v[30:31], v[132:135], off offset:2048
	v_lshlrev_b32_e32 v24, 16, v70
	v_and_b32_e32 v25, 0xffff0000, v70
	v_lshlrev_b32_e32 v26, 16, v71
	v_and_b32_e32 v27, 0xffff0000, v71
	v_pk_mul_f32 v[34:35], v[32:33], v[24:25] op_sel_hi:[0,1]
	v_pk_mul_f32 v[36:37], v[32:33], v[26:27] op_sel_hi:[0,1]
	v_pk_mul_f32 v[136:137], v[12:13], v[34:35]
	v_pk_mul_f32 v[138:139], v[14:15], v[36:37]
	global_store_dwordx4 v[30:31], v[136:139], off offset:3072
	s_add_i32 s2, s2, s6
	s_waitcnt vmcnt(31)
; __global__ void __launch_bounds__(512, 2) fwd_megakernel(Args a) {
;     ...
;         for (int row = blockIdx.x * 8 + wave; row < M; row += gridDim.x * 8) {
;             const float rstd = 1.0f / sqrtf(rss[row] * (1.f / D) + EPS); float* y = a.out + O_Y + (size_t)row * D + 4 * lane; const bf16_t* x3 = (const bf16_t*)(ws + WS_XG) + (size_t)row * D + 4 * lane;
; #pragma unroll
;             for (int j = 0; j < 4; ++j) { const u32x2 w = *(const u32x2*)(x3 + 256 * j);
;                 f32x4 v = {__uint_as_float(w.x << 16), __uint_as_float(w.x & 0xffff0000u), __uint_as_float(w.y << 16), __uint_as_float(w.y & 0xffff0000u)};
;                 *(f32x4*)(y + 256 * j) = v * rstd * gv[j]; }
	v_fmamk_f32 v23, v116, 0x3a800000, v16
	v_mul_f32_e32 v26, 0x4f800000, v23
	v_cmp_gt_f32_e32 vcc, s7, v23
	s_lshl_b64 s[0:1], s[2:3], 12
	v_lshl_add_u64 v[30:31], v[18:19], 0, s[0:1]
	v_cndmask_b32_e32 v23, v23, v26, vcc
	v_sqrt_f32_e32 v32, v23
	s_nop 1
	v_add_u32_e32 v33, -1, v32
	v_add_u32_e32 v34, 1, v32
	v_fma_f32 v35, -v33, v32, v23
	v_fma_f32 v36, -v34, v32, v23
	v_cmp_ge_f32_e64 s[0:1], 0, v35
	s_nop 1
	v_cndmask_b32_e64 v32, v32, v33, s[0:1]
	v_cmp_lt_f32_e64 s[0:1], 0, v36
	s_nop 1
	v_cndmask_b32_e64 v32, v32, v34, s[0:1]
	v_mul_f32_e32 v33, 0x37800000, v32
	v_cndmask_b32_e32 v32, v32, v33, vcc
	v_cmp_class_f32_e32 vcc, v23, v22
	s_nop 1
	v_cndmask_b32_e32 v23, v32, v23, vcc
	v_div_scale_f32 v32, s[0:1], v23, v23, 1.0
	v_rcp_f32_e32 v33, v32
	v_div_scale_f32 v34, vcc, 1.0, v23, 1.0
	v_fma_f32 v35, -v32, v33, 1.0
	v_fmac_f32_e32 v33, v35, v33
	v_mul_f32_e32 v35, v34, v33
	v_fma_f32 v36, -v32, v35, v34
	v_fmac_f32_e32 v35, v36, v33
	v_fma_f32 v32, -v32, v35, v34
	v_div_fmas_f32 v32, v32, v33, v35
	v_div_fixup_f32 v32, v32, v23, 1.0
	v_lshlrev_b32_e32 v24, 16, v72
	v_and_b32_e32 v25, 0xffff0000, v72
	v_lshlrev_b32_e32 v26, 16, v73
	v_and_b32_e32 v27, 0xffff0000, v73
	v_pk_mul_f32 v[34:35], v[32:33], v[24:25] op_sel_hi:[0,1]
	v_pk_mul_f32 v[36:37], v[32:33], v[26:27] op_sel_hi:[0,1]
	v_pk_mul_f32 v[124:125], v[0:1], v[34:35]
	v_pk_mul_f32 v[126:127], v[2:3], v[36:37]
	global_store_dwordx4 v[30:31], v[124:127], off
	v_lshlrev_b32_e32 v24, 16, v74
	v_and_b32_e32 v25, 0xffff0000, v74
	v_lshlrev_b32_e32 v26, 16, v75
	v_and_b32_e32 v27, 0xffff0000, v75
	v_pk_mul_f32 v[34:35], v[32:33], v[24:25] op_sel_hi:[0,1]
	v_pk_mul_f32 v[36:37], v[32:33], v[26:27] op_sel_hi:[0,1]
	v_pk_mul_f32 v[128:129], v[4:5], v[34:35]
	v_pk_mul_f32 v[130:131], v[6:7], v[36:37]
	global_store_dwordx4 v[30:31], v[128:131], off offset:1024
	v_lshlrev_b32_e32 v24, 16, v76
	v_and_b32_e32 v25, 0xffff0000, v76
	v_lshlrev_b32_e32 v26, 16, v77
	v_and_b32_e32 v27, 0xffff0000, v77
	v_pk_mul_f32 v[34:35], v[32:33], v[24:25] op_sel_hi:[0,1]
	v_pk_mul_f32 v[36:37], v[32:33], v[26:27] op_sel_hi:[0,1]
	v_pk_mul_f32 v[132:133], v[8:9], v[34:35]
	v_pk_mul_f32 v[134:135], v[10:11], v[36:37]
	global_store_dwordx4 v[30:31], v[132:135], off offset:2048
	v_lshlrev_b32_e32 v24, 16, v78
	v_and_b32_e32 v25, 0xffff0000, v78
	v_lshlrev_b32_e32 v26, 16, v79
	v_and_b32_e32 v27, 0xffff0000, v79
	v_pk_mul_f32 v[34:35], v[32:33], v[24:25] op_sel_hi:[0,1]
	v_pk_mul_f32 v[36:37], v[32:33], v[26:27] op_sel_hi:[0,1]
	v_pk_mul_f32 v[136:137], v[12:13], v[34:35]
	v_pk_mul_f32 v[138:139], v[14:15], v[36:37]
	global_store_dwordx4 v[30:31], v[136:139], off offset:3072
	s_add_i32 s2, s2, s6
	s_waitcnt vmcnt(30)
	v_fmamk_f32 v23, v117, 0x3a800000, v16
	v_mul_f32_e32 v26, 0x4f800000, v23
	v_cmp_gt_f32_e32 vcc, s7, v23
	s_lshl_b64 s[0:1], s[2:3], 12
	v_lshl_add_u64 v[30:31], v[18:19], 0, s[0:1]
	v_cndmask_b32_e32 v23, v23, v26, vcc
	v_sqrt_f32_e32 v32, v23
	s_nop 1
	v_add_u32_e32 v33, -1, v32
	v_add_u32_e32 v34, 1, v32
	v_fma_f32 v35, -v33, v32, v23
	v_fma_f32 v36, -v34, v32, v23
	v_cmp_ge_f32_e64 s[0:1], 0, v35
	s_nop 1
	v_cndmask_b32_e64 v32, v32, v33, s[0:1]
	v_cmp_lt_f32_e64 s[0:1], 0, v36
	s_nop 1
	v_cndmask_b32_e64 v32, v32, v34, s[0:1]
	v_mul_f32_e32 v33, 0x37800000, v32
	v_cndmask_b32_e32 v32, v32, v33, vcc
	v_cmp_class_f32_e32 vcc, v23, v22
	s_nop 1
	v_cndmask_b32_e32 v23, v32, v23, vcc
	v_div_scale_f32 v32, s[0:1], v23, v23, 1.0
	v_rcp_f32_e32 v33, v32
	v_div_scale_f32 v34, vcc, 1.0, v23, 1.0
	v_fma_f32 v35, -v32, v33, 1.0
	v_fmac_f32_e32 v33, v35, v33
	v_mul_f32_e32 v35, v34, v33
	v_fma_f32 v36, -v32, v35, v34
	v_fmac_f32_e32 v35, v36, v33
	v_fma_f32 v32, -v32, v35, v34
	v_div_fmas_f32 v32, v32, v33, v35
	v_div_fixup_f32 v32, v32, v23, 1.0
	v_lshlrev_b32_e32 v24, 16, v80
	v_and_b32_e32 v25, 0xffff0000, v80
	v_lshlrev_b32_e32 v26, 16, v81
	v_and_b32_e32 v27, 0xffff0000, v81
	v_pk_mul_f32 v[34:35], v[32:33], v[24:25] op_sel_hi:[0,1]
	v_pk_mul_f32 v[36:37], v[32:33], v[26:27] op_sel_hi:[0,1]
	v_pk_mul_f32 v[124:125], v[0:1], v[34:35]
	v_pk_mul_f32 v[126:127], v[2:3], v[36:37]
	global_store_dwordx4 v[30:31], v[124:127], off
	v_lshlrev_b32_e32 v24, 16, v82
	v_and_b32_e32 v25, 0xffff0000, v82
	v_lshlrev_b32_e32 v26, 16, v83
	v_and_b32_e32 v27, 0xffff0000, v83
	v_pk_mul_f32 v[34:35], v[32:33], v[24:25] op_sel_hi:[0,1]
	v_pk_mul_f32 v[36:37], v[32:33], v[26:27] op_sel_hi:[0,1]
	v_pk_mul_f32 v[128:129], v[4:5], v[34:35]
	v_pk_mul_f32 v[130:131], v[6:7], v[36:37]
	global_store_dwordx4 v[30:31], v[128:131], off offset:1024
	v_lshlrev_b32_e32 v24, 16, v84
	v_and_b32_e32 v25, 0xffff0000, v84
	v_lshlrev_b32_e32 v26, 16, v85
	v_and_b32_e32 v27, 0xffff0000, v85
	v_pk_mul_f32 v[34:35], v[32:33], v[24:25] op_sel_hi:[0,1]
	v_pk_mul_f32 v[36:37], v[32:33], v[26:27] op_sel_hi:[0,1]
	v_pk_mul_f32 v[132:133], v[8:9], v[34:35]
	v_pk_mul_f32 v[134:135], v[10:11], v[36:37]
	global_store_dwordx4 v[30:31], v[132:135], off offset:2048
	v_lshlrev_b32_e32 v24, 16, v86
	v_and_b32_e32 v25, 0xffff0000, v86
	v_lshlrev_b32_e32 v26, 16, v87
	v_and_b32_e32 v27, 0xffff0000, v87
	v_pk_mul_f32 v[34:35], v[32:33], v[24:25] op_sel_hi:[0,1]
	v_pk_mul_f32 v[36:37], v[32:33], v[26:27] op_sel_hi:[0,1]
	v_pk_mul_f32 v[136:137], v[12:13], v[34:35]
	v_pk_mul_f32 v[138:139], v[14:15], v[36:37]
	global_store_dwordx4 v[30:31], v[136:139], off offset:3072
	s_add_i32 s2, s2, s6
	s_waitcnt vmcnt(29)
; __global__ void __launch_bounds__(512, 2) fwd_megakernel(Args a) {
;     ...
;         for (int row = blockIdx.x * 8 + wave; row < M; row += gridDim.x * 8) {
;             const float rstd = 1.0f / sqrtf(rss[row] * (1.f / D) + EPS); float* y = a.out + O_Y + (size_t)row * D + 4 * lane; const bf16_t* x3 = (const bf16_t*)(ws + WS_XG) + (size_t)row * D + 4 * lane;
; #pragma unroll
;             for (int j = 0; j < 4; ++j) { const u32x2 w = *(const u32x2*)(x3 + 256 * j);
;                 f32x4 v = {__uint_as_float(w.x << 16), __uint_as_float(w.x & 0xffff0000u), __uint_as_float(w.y << 16), __uint_as_float(w.y & 0xffff0000u)};
;                 *(f32x4*)(y + 256 * j) = v * rstd * gv[j]; }
	v_fmamk_f32 v23, v118, 0x3a800000, v16
	v_mul_f32_e32 v26, 0x4f800000, v23
	v_cmp_gt_f32_e32 vcc, s7, v23
	s_lshl_b64 s[0:1], s[2:3], 12
	v_lshl_add_u64 v[30:31], v[18:19], 0, s[0:1]
	v_cndmask_b32_e32 v23, v23, v26, vcc
	v_sqrt_f32_e32 v32, v23
	s_nop 1
	v_add_u32_e32 v33, -1, v32
	v_add_u32_e32 v34, 1, v32
	v_fma_f32 v35, -v33, v32, v23
	v_fma_f32 v36, -v34, v32, v23
	v_cmp_ge_f32_e64 s[0:1], 0, v35
	s_nop 1
	v_cndmask_b32_e64 v32, v32, v33, s[0:1]
	v_cmp_lt_f32_e64 s[0:1], 0, v36
	s_nop 1
	v_cndmask_b32_e64 v32, v32, v34, s[0:1]
	v_mul_f32_e32 v33, 0x37800000, v32
	v_cndmask_b32_e32 v32, v32, v33, vcc
	v_cmp_class_f32_e32 vcc, v23, v22
	s_nop 1
	v_cndmask_b32_e32 v23, v32, v23, vcc
	v_div_scale_f32 v32, s[0:1], v23, v23, 1.0
	v_rcp_f32_e32 v33, v32
	v_div_scale_f32 v34, vcc, 1.0, v23, 1.0
	v_fma_f32 v35, -v32, v33, 1.0
	v_fmac_f32_e32 v33, v35, v33
	v_mul_f32_e32 v35, v34, v33
	v_fma_f32 v36, -v32, v35, v34
	v_fmac_f32_e32 v35, v36, v33
	v_fma_f32 v32, -v32, v35, v34
	v_div_fmas_f32 v32, v32, v33, v35
	v_div_fixup_f32 v32, v32, v23, 1.0
	v_lshlrev_b32_e32 v24, 16, v88
	v_and_b32_e32 v25, 0xffff0000, v88
	v_lshlrev_b32_e32 v26, 16, v89
	v_and_b32_e32 v27, 0xffff0000, v89
	v_pk_mul_f32 v[34:35], v[32:33], v[24:25] op_sel_hi:[0,1]
	v_pk_mul_f32 v[36:37], v[32:33], v[26:27] op_sel_hi:[0,1]
	v_pk_mul_f32 v[124:125], v[0:1], v[34:35]
	v_pk_mul_f32 v[126:127], v[2:3], v[36:37]
	global_store_dwordx4 v[30:31], v[124:127], off
	v_lshlrev_b32_e32 v24, 16, v90
	v_and_b32_e32 v25, 0xffff0000, v90
	v_lshlrev_b32_e32 v26, 16, v91
	v_and_b32_e32 v27, 0xffff0000, v91
	v_pk_mul_f32 v[34:35], v[32:33], v[24:25] op_sel_hi:[0,1]
	v_pk_mul_f32 v[36:37], v[32:33], v[26:27] op_sel_hi:[0,1]
	v_pk_mul_f32 v[128:129], v[4:5], v[34:35]
	v_pk_mul_f32 v[130:131], v[6:7], v[36:37]
	global_store_dwordx4 v[30:31], v[128:131], off offset:1024
	v_lshlrev_b32_e32 v24, 16, v92
	v_and_b32_e32 v25, 0xffff0000, v92
	v_lshlrev_b32_e32 v26, 16, v93
	v_and_b32_e32 v27, 0xffff0000, v93
	v_pk_mul_f32 v[34:35], v[32:33], v[24:25] op_sel_hi:[0,1]
	v_pk_mul_f32 v[36:37], v[32:33], v[26:27] op_sel_hi:[0,1]
	v_pk_mul_f32 v[132:133], v[8:9], v[34:35]
	v_pk_mul_f32 v[134:135], v[10:11], v[36:37]
	global_store_dwordx4 v[30:31], v[132:135], off offset:2048
	v_lshlrev_b32_e32 v24, 16, v94
	v_and_b32_e32 v25, 0xffff0000, v94
	v_lshlrev_b32_e32 v26, 16, v95
	v_and_b32_e32 v27, 0xffff0000, v95
	v_pk_mul_f32 v[34:35], v[32:33], v[24:25] op_sel_hi:[0,1]
	v_pk_mul_f32 v[36:37], v[32:33], v[26:27] op_sel_hi:[0,1]
	v_pk_mul_f32 v[136:137], v[12:13], v[34:35]
	v_pk_mul_f32 v[138:139], v[14:15], v[36:37]
	global_store_dwordx4 v[30:31], v[136:139], off offset:3072
	s_add_i32 s2, s2, s6
	s_waitcnt vmcnt(28)
	v_fmamk_f32 v23, v119, 0x3a800000, v16
	v_mul_f32_e32 v26, 0x4f800000, v23
	v_cmp_gt_f32_e32 vcc, s7, v23
	s_lshl_b64 s[0:1], s[2:3], 12
	v_lshl_add_u64 v[30:31], v[18:19], 0, s[0:1]
	v_cndmask_b32_e32 v23, v23, v26, vcc
	v_sqrt_f32_e32 v32, v23
	s_nop 1
	v_add_u32_e32 v33, -1, v32
	v_add_u32_e32 v34, 1, v32
	v_fma_f32 v35, -v33, v32, v23
	v_fma_f32 v36, -v34, v32, v23
	v_cmp_ge_f32_e64 s[0:1], 0, v35
	s_nop 1
	v_cndmask_b32_e64 v32, v32, v33, s[0:1]
	v_cmp_lt_f32_e64 s[0:1], 0, v36
	s_nop 1
	v_cndmask_b32_e64 v32, v32, v34, s[0:1]
	v_mul_f32_e32 v33, 0x37800000, v32
	v_cndmask_b32_e32 v32, v32, v33, vcc
	v_cmp_class_f32_e32 vcc, v23, v22
	s_nop 1
	v_cndmask_b32_e32 v23, v32, v23, vcc
	v_div_scale_f32 v32, s[0:1], v23, v23, 1.0
	v_rcp_f32_e32 v33, v32
	v_div_scale_f32 v34, vcc, 1.0, v23, 1.0
	v_fma_f32 v35, -v32, v33, 1.0
	v_fmac_f32_e32 v33, v35, v33
	v_mul_f32_e32 v35, v34, v33
	v_fma_f32 v36, -v32, v35, v34
	v_fmac_f32_e32 v35, v36, v33
	v_fma_f32 v32, -v32, v35, v34
	v_div_fmas_f32 v32, v32, v33, v35
	v_div_fixup_f32 v32, v32, v23, 1.0
	v_lshlrev_b32_e32 v24, 16, v96
	v_and_b32_e32 v25, 0xffff0000, v96
	v_lshlrev_b32_e32 v26, 16, v97
	v_and_b32_e32 v27, 0xffff0000, v97
	v_pk_mul_f32 v[34:35], v[32:33], v[24:25] op_sel_hi:[0,1]
	v_pk_mul_f32 v[36:37], v[32:33], v[26:27] op_sel_hi:[0,1]
	v_pk_mul_f32 v[124:125], v[0:1], v[34:35]
	v_pk_mul_f32 v[126:127], v[2:3], v[36:37]
	global_store_dwordx4 v[30:31], v[124:127], off
	v_lshlrev_b32_e32 v24, 16, v98
	v_and_b32_e32 v25, 0xffff0000, v98
	v_lshlrev_b32_e32 v26, 16, v99
	v_and_b32_e32 v27, 0xffff0000, v99
	v_pk_mul_f32 v[34:35], v[32:33], v[24:25] op_sel_hi:[0,1]
	v_pk_mul_f32 v[36:37], v[32:33], v[26:27] op_sel_hi:[0,1]
	v_pk_mul_f32 v[128:129], v[4:5], v[34:35]
	v_pk_mul_f32 v[130:131], v[6:7], v[36:37]
	global_store_dwordx4 v[30:31], v[128:131], off offset:1024
	v_lshlrev_b32_e32 v24, 16, v100
	v_and_b32_e32 v25, 0xffff0000, v100
	v_lshlrev_b32_e32 v26, 16, v101
	v_and_b32_e32 v27, 0xffff0000, v101
	v_pk_mul_f32 v[34:35], v[32:33], v[24:25] op_sel_hi:[0,1]
	v_pk_mul_f32 v[36:37], v[32:33], v[26:27] op_sel_hi:[0,1]
	v_pk_mul_f32 v[132:133], v[8:9], v[34:35]
	v_pk_mul_f32 v[134:135], v[10:11], v[36:37]
	global_store_dwordx4 v[30:31], v[132:135], off offset:2048
	v_lshlrev_b32_e32 v24, 16, v102
	v_and_b32_e32 v25, 0xffff0000, v102
	v_lshlrev_b32_e32 v26, 16, v103
	v_and_b32_e32 v27, 0xffff0000, v103
	v_pk_mul_f32 v[34:35], v[32:33], v[24:25] op_sel_hi:[0,1]
	v_pk_mul_f32 v[36:37], v[32:33], v[26:27] op_sel_hi:[0,1]
	v_pk_mul_f32 v[136:137], v[12:13], v[34:35]
	v_pk_mul_f32 v[138:139], v[14:15], v[36:37]
	global_store_dwordx4 v[30:31], v[136:139], off offset:3072
	s_add_i32 s2, s2, s6
	s_and_b64 vcc, exec, s[10:11]
	s_cbranch_vccz .LBB0_1010
; __global__ void __launch_bounds__(512, 2) fwd_megakernel(Args a) {
;     ...
;         for (int row = blockIdx.x * 8 + wave; row < M; row += gridDim.x * 8) {
;             const float rstd = 1.0f / sqrtf(rss[row] * (1.f / D) + EPS); float* y = a.out + O_Y + (size_t)row * D + 4 * lane; const bf16_t* x3 = (const bf16_t*)(ws + WS_XG) + (size_t)row * D + 4 * lane;
; #pragma unroll
;             for (int j = 0; j < 4; ++j) { const u32x2 w = *(const u32x2*)(x3 + 256 * j);
;                 f32x4 v = {__uint_as_float(w.x << 16), __uint_as_float(w.x & 0xffff0000u), __uint_as_float(w.y << 16), __uint_as_float(w.y & 0xffff0000u)};
;                 *(f32x4*)(y + 256 * j) = v * rstd * gv[j]; }
	v_fmamk_f32 v23, v120, 0x3a800000, v16
	v_mul_f32_e32 v26, 0x4f800000, v23
	v_cmp_gt_f32_e32 vcc, s7, v23
	s_lshl_b64 s[0:1], s[2:3], 12
	v_lshl_add_u64 v[30:31], v[18:19], 0, s[0:1]
	v_cndmask_b32_e32 v23, v23, v26, vcc
	v_sqrt_f32_e32 v32, v23
	s_nop 1
	v_add_u32_e32 v33, -1, v32
	v_add_u32_e32 v34, 1, v32
	v_fma_f32 v35, -v33, v32, v23
	v_fma_f32 v36, -v34, v32, v23
	v_cmp_ge_f32_e64 s[0:1], 0, v35
	s_nop 1
	v_cndmask_b32_e64 v32, v32, v33, s[0:1]
	v_cmp_lt_f32_e64 s[0:1], 0, v36
	s_nop 1
	v_cndmask_b32_e64 v32, v32, v34, s[0:1]
	v_mul_f32_e32 v33, 0x37800000, v32
	v_cndmask_b32_e32 v32, v32, v33, vcc
	v_cmp_class_f32_e32 vcc, v23, v22
	s_nop 1
	v_cndmask_b32_e32 v23, v32, v23, vcc
	v_div_scale_f32 v32, s[0:1], v23, v23, 1.0
	v_rcp_f32_e32 v33, v32
	v_div_scale_f32 v34, vcc, 1.0, v23, 1.0
	v_fma_f32 v35, -v32, v33, 1.0
	v_fmac_f32_e32 v33, v35, v33
	v_mul_f32_e32 v35, v34, v33
	v_fma_f32 v36, -v32, v35, v34
	v_fmac_f32_e32 v35, v36, v33
	v_fma_f32 v32, -v32, v35, v34
	v_div_fmas_f32 v32, v32, v33, v35
	v_div_fixup_f32 v32, v32, v23, 1.0
	v_lshlrev_b32_e32 v24, 16, v104
	v_and_b32_e32 v25, 0xffff0000, v104
	v_lshlrev_b32_e32 v26, 16, v105
	v_and_b32_e32 v27, 0xffff0000, v105
	v_pk_mul_f32 v[34:35], v[32:33], v[24:25] op_sel_hi:[0,1]
	v_pk_mul_f32 v[36:37], v[32:33], v[26:27] op_sel_hi:[0,1]
	v_pk_mul_f32 v[124:125], v[0:1], v[34:35]
	v_pk_mul_f32 v[126:127], v[2:3], v[36:37]
	global_store_dwordx4 v[30:31], v[124:127], off
	v_lshlrev_b32_e32 v24, 16, v106
	v_and_b32_e32 v25, 0xffff0000, v106
	v_lshlrev_b32_e32 v26, 16, v107
	v_and_b32_e32 v27, 0xffff0000, v107
	v_pk_mul_f32 v[34:35], v[32:33], v[24:25] op_sel_hi:[0,1]
	v_pk_mul_f32 v[36:37], v[32:33], v[26:27] op_sel_hi:[0,1]
	v_pk_mul_f32 v[128:129], v[4:5], v[34:35]
	v_pk_mul_f32 v[130:131], v[6:7], v[36:37]
	global_store_dwordx4 v[30:31], v[128:131], off offset:1024
	v_lshlrev_b32_e32 v24, 16, v108
	v_and_b32_e32 v25, 0xffff0000, v108
	v_lshlrev_b32_e32 v26, 16, v109
	v_and_b32_e32 v27, 0xffff0000, v109
	v_pk_mul_f32 v[34:35], v[32:33], v[24:25] op_sel_hi:[0,1]
	v_pk_mul_f32 v[36:37], v[32:33], v[26:27] op_sel_hi:[0,1]
	v_pk_mul_f32 v[132:133], v[8:9], v[34:35]
	v_pk_mul_f32 v[134:135], v[10:11], v[36:37]
	global_store_dwordx4 v[30:31], v[132:135], off offset:2048
	v_lshlrev_b32_e32 v24, 16, v110
	v_and_b32_e32 v25, 0xffff0000, v110
	v_lshlrev_b32_e32 v26, 16, v111
	v_and_b32_e32 v27, 0xffff0000, v111
	v_pk_mul_f32 v[34:35], v[32:33], v[24:25] op_sel_hi:[0,1]
	v_pk_mul_f32 v[36:37], v[32:33], v[26:27] op_sel_hi:[0,1]
	v_pk_mul_f32 v[136:137], v[12:13], v[34:35]
	v_pk_mul_f32 v[138:139], v[14:15], v[36:37]
	global_store_dwordx4 v[30:31], v[136:139], off offset:3072
